# HGRN scan loop: drop per-step v_mov copies via op_sel, merge dpp-mov plus masked add into one dpp add, remove early lgkmcnt wait
# baseline (speedup 1.0000x reference)
; #define HG_LD(X, tl_) do { const float* f_ = sF + (tl_) * 128 + seg * 4; const float* q_ = sQ + (tl_) * 128 + seg * 4;   \
;                 X##f0 = *(const f32x4*)(f_); X##f1 = *(const f32x4*)(f_ + 64); X##q0 = *(const f32x4*)(q_); X##q1 = *(const f32x4*)(q_ + 64); \
;                 X##va = sDV[(tl_) * 64 + cp]; X##vb = sDV[(tl_) * 64 + 32 + cp]; } while (0)
; __device__ __forceinline__ void phase_hgrn(KP P, int l_, unsigned char* shm) {
;     ...
;             {
;                 f32x4 Af0, Af1, Aq0, Aq1; float Ava, Avb;
;                 f32x4 Bf0, Bf1, Bq0, Bq1; float Bva, Bvb;
;                 HG_LD(A, 0);
; #pragma unroll 2
;                 for (int tl = 0; tl < T; tl += 2) {
;                     HG_LD(B, tl + 1);
;                     HG_STEP(A, tl);
;                     HG_LD(A, tl + 2);
;                     HG_STEP(B, tl + 1);
;                 }
.LBB0_2162:
	ds_read_b128 v[18:21], v111
	ds_read_b128 v[14:17], v111 offset:256
	ds_read_b128 v[10:13], v111 offset:16384
	ds_read_b128 v[6:9], v111 offset:16640
	ds_read2_b32 v[78:79], v116 offset1:32
	s_mov_b32 s17, -2
	v_mov_b32_e32 v129, v110
	v_mov_b32_e32 v130, v109
	v_mov_b32_e32 v131, v108
	v_mov_b32_e32 v132, v107
	s_waitcnt lgkmcnt(0)
	s_branch .LBB0_2164

; #define HG_LD(X, tl_) do { const float* f_ = sF + (tl_) * 128 + seg * 4; const float* q_ = sQ + (tl_) * 128 + seg * 4;   \
;                 X##f0 = *(const f32x4*)(f_); X##f1 = *(const f32x4*)(f_ + 64); X##q0 = *(const f32x4*)(q_); X##q1 = *(const f32x4*)(q_ + 64); \
;                 X##va = sDV[(tl_) * 64 + cp]; X##vb = sDV[(tl_) * 64 + 32 + cp]; } while (0)
; __device__ __forceinline__ void phase_hgrn(KP P, int l_, unsigned char* shm) {
;     ...
;             {
;                 f32x4 Af0, Af1, Aq0, Aq1; float Ava, Avb;
;                 f32x4 Bf0, Bf1, Bq0, Bq1; float Bva, Bvb;
;                 HG_LD(A, 0);
; #pragma unroll 2
;                 for (int tl = 0; tl < T; tl += 2) {
;                     HG_LD(B, tl + 1);
;                     HG_STEP(A, tl);
;                     HG_LD(A, tl + 2);
;                     HG_STEP(B, tl + 1);
;                 }
.LBB0_2164:
	ds_read_b128 v[34:37], v129
	ds_read_b128 v[30:33], v129 offset:256
	ds_read_b128 v[26:29], v129 offset:16384
	ds_read_b128 v[22:25], v129 offset:16640
	ds_read2_b32 v[80:81], v130 offset1:32
	s_waitcnt lgkmcnt(8)
	v_pk_fma_f32 v[70:71], v[20:21], v[70:71], v[78:79] op_sel_hi:[1,1,0]
	v_pk_fma_f32 v[76:77], v[20:21], v[76:77], v[78:79] op_sel:[0,0,1]
	v_pk_fma_f32 v[64:65], v[18:19], v[64:65], v[78:79] op_sel_hi:[1,1,0]
	v_pk_fma_f32 v[82:83], v[18:19], v[62:63], v[78:79] op_sel:[0,0,1]
	s_waitcnt lgkmcnt(7)
	v_pk_fma_f32 v[68:69], v[14:15], v[68:69], v[78:79] op_sel_hi:[1,1,0]
	v_pk_fma_f32 v[74:75], v[14:15], v[74:75], v[78:79] op_sel:[0,0,1]
	v_pk_fma_f32 v[66:67], v[16:17], v[66:67], v[78:79] op_sel_hi:[1,1,0]
	v_pk_fma_f32 v[72:73], v[16:17], v[72:73], v[78:79] op_sel:[0,0,1]
	s_waitcnt lgkmcnt(6)
	v_pk_mul_f32 v[14:15], v[12:13], v[70:71]
	v_pk_mul_f32 v[12:13], v[12:13], v[76:77]
	v_pk_fma_f32 v[14:15], v[10:11], v[64:65], v[14:15]
	v_pk_fma_f32 v[10:11], v[10:11], v[82:83], v[12:13]
	s_waitcnt lgkmcnt(5)
	v_pk_mul_f32 v[12:13], v[8:9], v[66:67]
	v_pk_mul_f32 v[8:9], v[8:9], v[72:73]
	v_pk_fma_f32 v[12:13], v[6:7], v[68:69], v[12:13]
	v_pk_fma_f32 v[6:7], v[6:7], v[74:75], v[8:9]
	v_pk_add_f32 v[12:13], v[12:13], v[14:15]
	v_pk_add_f32 v[6:7], v[6:7], v[10:11]
	v_add_f32_e32 v4, v12, v13
	v_add_f32_e32 v6, v6, v7
	s_nop 0
	v_add_f32_dpp v4, v4, v4 quad_perm:[1,0,3,2] row_mask:0xf bank_mask:0xf bound_ctrl:1
	v_add_f32_dpp v6, v6, v6 quad_perm:[1,0,3,2] row_mask:0xf bank_mask:0xf bound_ctrl:1
	s_nop 0
	v_add_f32_dpp v4, v4, v4 quad_perm:[2,3,0,1] row_mask:0xf bank_mask:0xf bound_ctrl:1
	v_add_f32_dpp v6, v6, v6 quad_perm:[2,3,0,1] row_mask:0xf bank_mask:0xf bound_ctrl:1
	s_and_saveexec_b64 s[22:23], s[8:9]
	s_cbranch_execz .LBB0_2166
	ds_write_b32 v132, v4
	ds_write_b32 v131, v6
.LBB0_2166:
	s_or_b64 exec, exec, s[22:23]
	s_waitcnt lgkmcnt(2)
	ds_read_b128 v[18:21], v129 offset:512
	ds_read_b128 v[14:17], v129 offset:768
	ds_read_b128 v[10:13], v129 offset:16896
	ds_read_b128 v[6:9], v129 offset:17152
	ds_read2_b32 v[62:63], v130 offset0:64 offset1:96
	v_pk_fma_f32 v[70:71], v[70:71], v[36:37], v[80:81] op_sel_hi:[1,1,0]
	v_pk_fma_f32 v[76:77], v[36:37], v[76:77], v[80:81] op_sel:[0,0,1]
	v_pk_fma_f32 v[64:65], v[64:65], v[34:35], v[80:81] op_sel_hi:[1,1,0]
	v_pk_fma_f32 v[78:79], v[34:35], v[82:83], v[80:81] op_sel:[0,0,1]
	v_pk_fma_f32 v[82:83], v[68:69], v[30:31], v[80:81] op_sel_hi:[1,1,0]
	v_pk_fma_f32 v[84:85], v[74:75], v[30:31], v[80:81] op_sel:[0,0,1]
	v_pk_fma_f32 v[86:87], v[66:67], v[32:33], v[80:81] op_sel_hi:[1,1,0]
	v_pk_fma_f32 v[88:89], v[72:73], v[32:33], v[80:81] op_sel:[0,0,1]
	v_pk_mul_f32 v[30:31], v[28:29], v[70:71]
	v_pk_mul_f32 v[28:29], v[28:29], v[76:77]
	v_pk_fma_f32 v[30:31], v[26:27], v[64:65], v[30:31]
	v_pk_fma_f32 v[26:27], v[26:27], v[78:79], v[28:29]
	v_pk_mul_f32 v[28:29], v[24:25], v[86:87]
	v_pk_mul_f32 v[24:25], v[24:25], v[88:89]
	v_pk_fma_f32 v[28:29], v[22:23], v[82:83], v[28:29]
	v_pk_fma_f32 v[22:23], v[22:23], v[84:85], v[24:25]
	v_pk_add_f32 v[28:29], v[30:31], v[28:29]
	v_pk_add_f32 v[22:23], v[26:27], v[22:23]
	v_add_f32_e32 v4, v28, v29
	v_add_f32_e32 v22, v22, v23
	s_nop 0
	v_add_f32_dpp v4, v4, v4 quad_perm:[1,0,3,2] row_mask:0xf bank_mask:0xf bound_ctrl:1
	v_add_f32_dpp v22, v22, v22 quad_perm:[1,0,3,2] row_mask:0xf bank_mask:0xf bound_ctrl:1
	s_nop 0
	v_add_f32_dpp v4, v4, v4 quad_perm:[2,3,0,1] row_mask:0xf bank_mask:0xf bound_ctrl:1
	v_add_f32_dpp v22, v22, v22 quad_perm:[2,3,0,1] row_mask:0xf bank_mask:0xf bound_ctrl:1
	s_and_saveexec_b64 s[22:23], s[8:9]
	s_cbranch_execz .LBB0_2168
	ds_write_b32 v132, v4 offset:1024
	ds_write_b32 v131, v22 offset:1024
; #define HG_LD(X, tl_) do { const float* f_ = sF + (tl_) * 128 + seg * 4; const float* q_ = sQ + (tl_) * 128 + seg * 4;   \
;                 X##f0 = *(const f32x4*)(f_); X##f1 = *(const f32x4*)(f_ + 64); X##q0 = *(const f32x4*)(q_); X##q1 = *(const f32x4*)(q_ + 64); \
;                 X##va = sDV[(tl_) * 64 + cp]; X##vb = sDV[(tl_) * 64 + 32 + cp]; } while (0)
; __device__ __forceinline__ void phase_hgrn(KP P, int l_, unsigned char* shm) {
;     ...
;             {
;                 f32x4 Af0, Af1, Aq0, Aq1; float Ava, Avb;
;                 f32x4 Bf0, Bf1, Bq0, Bq1; float Bva, Bvb;
;                 HG_LD(A, 0);
; #pragma unroll 2
;                 for (int tl = 0; tl < T; tl += 2) {
;                     HG_LD(B, tl + 1);
;                     HG_STEP(A, tl);
;                     HG_LD(A, tl + 2);
;                     HG_STEP(B, tl + 1);
;                 }
.LBB0_2168:
	s_or_b64 exec, exec, s[22:23]
	s_waitcnt lgkmcnt(2)
	ds_read_b128 v[34:37], v129 offset:1024
	ds_read_b128 v[30:33], v129 offset:1280
	ds_read_b128 v[26:29], v129 offset:17408
	ds_read_b128 v[22:25], v129 offset:17664
	ds_read2_b32 v[66:67], v130 offset0:128 offset1:160
	v_pk_fma_f32 v[70:71], v[20:21], v[70:71], v[62:63] op_sel_hi:[1,1,0]
	v_pk_fma_f32 v[72:73], v[20:21], v[76:77], v[62:63] op_sel:[0,0,1]
	v_pk_fma_f32 v[64:65], v[18:19], v[64:65], v[62:63] op_sel_hi:[1,1,0]
	v_pk_fma_f32 v[68:69], v[18:19], v[78:79], v[62:63] op_sel:[0,0,1]
	v_pk_fma_f32 v[74:75], v[14:15], v[82:83], v[62:63] op_sel_hi:[1,1,0]
	v_pk_fma_f32 v[80:81], v[14:15], v[84:85], v[62:63] op_sel:[0,0,1]
	v_pk_fma_f32 v[82:83], v[16:17], v[86:87], v[62:63] op_sel_hi:[1,1,0]
	v_pk_fma_f32 v[84:85], v[16:17], v[88:89], v[62:63] op_sel:[0,0,1]
	v_pk_mul_f32 v[14:15], v[12:13], v[70:71]
	v_pk_mul_f32 v[12:13], v[12:13], v[72:73]
	v_pk_fma_f32 v[14:15], v[10:11], v[64:65], v[14:15]
	v_pk_fma_f32 v[10:11], v[10:11], v[68:69], v[12:13]
	v_pk_mul_f32 v[12:13], v[8:9], v[82:83]
	v_pk_mul_f32 v[8:9], v[8:9], v[84:85]
	v_pk_fma_f32 v[12:13], v[6:7], v[74:75], v[12:13]
	v_pk_fma_f32 v[6:7], v[6:7], v[80:81], v[8:9]
	v_pk_add_f32 v[12:13], v[12:13], v[14:15]
	v_pk_add_f32 v[6:7], v[6:7], v[10:11]
	v_add_f32_e32 v4, v12, v13
	v_add_f32_e32 v6, v6, v7
	s_nop 0
	v_add_f32_dpp v4, v4, v4 quad_perm:[1,0,3,2] row_mask:0xf bank_mask:0xf bound_ctrl:1
	v_add_f32_dpp v6, v6, v6 quad_perm:[1,0,3,2] row_mask:0xf bank_mask:0xf bound_ctrl:1
	s_nop 0
	v_add_f32_dpp v4, v4, v4 quad_perm:[2,3,0,1] row_mask:0xf bank_mask:0xf bound_ctrl:1
	v_add_f32_dpp v6, v6, v6 quad_perm:[2,3,0,1] row_mask:0xf bank_mask:0xf bound_ctrl:1
	s_and_saveexec_b64 s[22:23], s[8:9]
	s_cbranch_execz .LBB0_2170
	ds_write_b32 v132, v4 offset:2048
	ds_write_b32 v131, v6 offset:2048
.LBB0_2170:
	s_or_b64 exec, exec, s[22:23]
	s_waitcnt lgkmcnt(2)
	v_pk_fma_f32 v[70:71], v[70:71], v[36:37], v[66:67] op_sel_hi:[1,1,0]
	v_pk_fma_f32 v[76:77], v[36:37], v[72:73], v[66:67] op_sel:[0,0,1]
	v_pk_fma_f32 v[64:65], v[64:65], v[34:35], v[66:67] op_sel_hi:[1,1,0]
	v_pk_fma_f32 v[62:63], v[34:35], v[68:69], v[66:67] op_sel:[0,0,1]
	v_pk_fma_f32 v[68:69], v[74:75], v[30:31], v[66:67] op_sel_hi:[1,1,0]
	v_pk_fma_f32 v[74:75], v[80:81], v[30:31], v[66:67] op_sel:[0,0,1]
	v_pk_fma_f32 v[72:73], v[84:85], v[32:33], v[66:67] op_sel:[0,0,1]
	v_pk_fma_f32 v[66:67], v[82:83], v[32:33], v[66:67] op_sel_hi:[1,1,0]
	v_pk_mul_f32 v[30:31], v[28:29], v[70:71]
	v_pk_mul_f32 v[28:29], v[28:29], v[76:77]
	v_pk_fma_f32 v[30:31], v[26:27], v[64:65], v[30:31]
	v_pk_fma_f32 v[26:27], v[26:27], v[62:63], v[28:29]
	v_pk_mul_f32 v[28:29], v[24:25], v[66:67]
	v_pk_mul_f32 v[24:25], v[24:25], v[72:73]
	v_pk_fma_f32 v[28:29], v[22:23], v[68:69], v[28:29]
	v_pk_fma_f32 v[22:23], v[22:23], v[74:75], v[24:25]
	v_pk_add_f32 v[28:29], v[30:31], v[28:29]
	v_pk_add_f32 v[22:23], v[26:27], v[22:23]
	v_add_f32_e32 v24, v28, v29
	v_add_f32_e32 v23, v22, v23
	ds_read2_b32 v[78:79], v130 offset0:192 offset1:224
	ds_read_b128 v[18:21], v129 offset:1536
	ds_read_b128 v[14:17], v129 offset:1792
	ds_read_b128 v[10:13], v129 offset:17920
	ds_read_b128 v[6:9], v129 offset:18176
	v_add_f32_dpp v22, v24, v24 quad_perm:[1,0,3,2] row_mask:0xf bank_mask:0xf bound_ctrl:1
	v_add_f32_dpp v23, v23, v23 quad_perm:[1,0,3,2] row_mask:0xf bank_mask:0xf bound_ctrl:1
	s_nop 0
	v_add_f32_dpp v22, v22, v22 quad_perm:[2,3,0,1] row_mask:0xf bank_mask:0xf bound_ctrl:1
	v_add_f32_dpp v23, v23, v23 quad_perm:[2,3,0,1] row_mask:0xf bank_mask:0xf bound_ctrl:1
	s_and_saveexec_b64 s[22:23], s[8:9]
	s_cbranch_execz .LBB0_2163
	ds_write_b32 v132, v22 offset:3072
	ds_write_b32 v131, v23 offset:3072
	s_branch .LBB0_2163
